# GLU epilogue: the eight z_s loads issued together up front with counted vmcnt(7) at each use (was load -> vmcnt(0) per 16-row group)
# speedup vs baseline: 1.0587x; 1.0005x over previous
; __device__ __forceinline__ unsigned cvt_pk_bf16(float lo, float hi) { unsigned r; asm volatile("v_cvt_pk_bf16_f32 %0, %1, %2" : "=v"(r) : "v"(lo), "v"(hi)); return r; }
; __device__ __forceinline__ float bflo(unsigned w) { return __uint_as_float(w << 16); }
; __device__ __forceinline__ float bfhi(unsigned w) { return __uint_as_float(w & 0xffff0000u); }
; __device__ __forceinline__ float silu_f(float z) { return z / (1.0f + __expf(-z)); }
; __device__ __forceinline__ float sigmoid_f(float z) { return 1.0f / (1.0f + __expf(-z)); }
;     __device__ __forceinline__ void operator()(const AccT& acc, const Unit& u, int wr, int wc, int fr, int fq) const {
;         bf16_t* OCAT = (bf16_t*)(ws + WS_H); const bf16_t* PROJ = (const bf16_t*)(ws + WS_PROJ);
;         const int lc = u.pn * 128 + wc * 32 + 8 * fq;
;         const f32x4 bl0 = *(const f32x4*)(bglu + lc), bl1 = *(const f32x4*)(bglu + lc + 4), bg0 = *(const f32x4*)(bglu + 1024 + lc), bg1 = *(const f32x4*)(bglu + 1024 + lc + 4);
; #pragma unroll
;         for (int ai = 0; ai < 2; ++ai)
; #pragma unroll
;             for (int m = 0; m < 4; ++m) {
;                 const int row = u.pm * 256 + ai * 128 + wr * 64 + m * 16 + fr;
;                 const u32x4 z = *(const u32x4*)(PROJ + (size_t)row * PP + C_ZS + lc);
;                 const f32x4 l0 = acc[ai][0][m][0] + bl0, l1 = acc[ai][0][m][1] + bl1, g0 = acc[ai][1][m][0] + bg0, g1 = acc[ai][1][m][1] + bg1;
;                 float o[8];
;                 o[0] = l0[0] * sigmoid_f(g0[0]) * silu_f(bflo(z.x)); o[1] = l0[1] * sigmoid_f(g0[1]) * silu_f(bfhi(z.x));
;                 o[2] = l0[2] * sigmoid_f(g0[2]) * silu_f(bflo(z.y)); o[3] = l0[3] * sigmoid_f(g0[3]) * silu_f(bfhi(z.y));
;                 o[4] = l1[0] * sigmoid_f(g1[0]) * silu_f(bflo(z.z)); o[5] = l1[1] * sigmoid_f(g1[1]) * silu_f(bfhi(z.z));
;                 o[6] = l1[2] * sigmoid_f(g1[2]) * silu_f(bflo(z.w)); o[7] = l1[3] * sigmoid_f(g1[3]) * silu_f(bfhi(z.w));
;                 u32x4 w; w.x = cvt_pk_bf16(o[0], o[1]); w.y = cvt_pk_bf16(o[2], o[3]); w.z = cvt_pk_bf16(o[4], o[5]); w.w = cvt_pk_bf16(o[6], o[7]);
;                 *(u32x4*)(OCAT + (size_t)row * 2048 + 1024 + lc) = w;
;                 if (m == 3) asm volatile("" ::: "memory");
;             }
.LBB0_609:
	v_lshl_or_b32 v128, s38, 7, v166
	v_ashrrev_i32_e32 v129, 31, v128
	v_lshl_add_u32 v168, s37, 8, v164
	v_mov_b64_e32 v[160:161], s[6:7]
	v_lshlrev_b64 v[16:17], 2, v[128:129]
	v_mad_i64_i32 v[162:163], s[30:31], v168, s52, v[160:161]
	v_lshlrev_b64 v[158:159], 1, v[128:129]
	v_lshl_add_u64 v[18:19], s[16:17], 0, v[16:17]
	v_lshl_add_u64 v[20:21], s[18:19], 0, v[16:17]
	v_lshl_add_u64 v[128:129], v[162:163], 0, v[158:159]
	global_load_dwordx4 v[24:27], v[18:19], off offset:16
	global_load_dwordx4 v[28:31], v[18:19], off
	s_nop 0
	global_load_dwordx4 v[16:19], v[20:21], off offset:16
	s_nop 0
	global_load_dwordx4 v[20:23], v[20:21], off
	v_add_co_u32_e32 v128, vcc, s63, v128
	s_waitcnt vmcnt(0)
	v_pk_add_f32 v[140:141], v[140:141], v[24:25]
	v_addc_co_u32_e32 v129, vcc, 0, v129, vcc
	s_mov_b32 s82, 0x28000
	s_mov_b32 s83, 0
	v_lshl_add_u64 v[176:177], v[128:129], 0, s[82:83]
	s_mov_b32 s82, 0x50000
	s_mov_b32 s83, 0
	v_lshl_add_u64 v[180:181], v[128:129], 0, s[82:83]
	s_mov_b32 s82, 0x78000
	s_mov_b32 s83, 0
	v_lshl_add_u64 v[184:185], v[128:129], 0, s[82:83]
	s_mov_b32 s82, 0x140000
	s_mov_b32 s83, 0
	v_lshl_add_u64 v[188:189], v[128:129], 0, s[82:83]
	s_mov_b32 s82, 0x168000
	s_mov_b32 s83, 0
	v_lshl_add_u64 v[192:193], v[128:129], 0, s[82:83]
	s_mov_b32 s82, 0x190000
	s_mov_b32 s83, 0
	v_lshl_add_u64 v[196:197], v[128:129], 0, s[82:83]
	s_mov_b32 s82, 0x1b8000
	s_mov_b32 s83, 0
	v_lshl_add_u64 v[200:201], v[128:129], 0, s[82:83]
	global_load_dwordx4 v[128:131], v[128:129], off
	global_load_dwordx4 v[176:179], v[176:177], off
	global_load_dwordx4 v[180:183], v[180:181], off
	global_load_dwordx4 v[184:187], v[184:185], off
	global_load_dwordx4 v[188:191], v[188:189], off
	global_load_dwordx4 v[192:195], v[192:193], off
	global_load_dwordx4 v[196:199], v[196:197], off
	global_load_dwordx4 v[200:203], v[200:201], off
	v_pk_add_f32 v[136:137], v[136:137], v[20:21]
	v_pk_add_f32 v[144:145], v[144:145], v[28:29]
	v_mul_f32_e32 v136, 0xbfb8aa3b, v136
	v_exp_f32_e32 v170, v136
	v_pk_add_f32 v[138:139], v[138:139], v[22:23]
	v_pk_add_f32 v[146:147], v[146:147], v[30:31]
	v_pk_add_f32 v[132:133], v[132:133], v[16:17]
	v_pk_add_f32 v[134:135], v[134:135], v[18:19]
	v_mul_f32_e32 v132, 0xbfb8aa3b, v132
	v_pk_add_f32 v[142:143], v[142:143], v[26:27]
	v_pk_add_f32 v[116:117], v[116:117], v[20:21]
	v_pk_add_f32 v[124:125], v[124:125], v[28:29]
	v_mul_f32_e32 v116, 0xbfb8aa3b, v116
	v_mul_f32_e32 v117, 0xbfb8aa3b, v117
	v_pk_add_f32 v[118:119], v[118:119], v[22:23]
	v_pk_add_f32 v[126:127], v[126:127], v[30:31]
	v_mul_f32_e32 v118, 0xbfb8aa3b, v118
	v_mul_f32_e32 v119, 0xbfb8aa3b, v119
	v_pk_add_f32 v[112:113], v[112:113], v[16:17]
	v_pk_add_f32 v[120:121], v[120:121], v[24:25]
	v_mul_f32_e32 v112, 0xbfb8aa3b, v112
	v_pk_add_f32 v[114:115], v[114:115], v[18:19]
	v_pk_add_f32 v[122:123], v[122:123], v[26:27]
	v_pk_add_f32 v[100:101], v[100:101], v[20:21]
	v_pk_add_f32 v[108:109], v[108:109], v[28:29]
	v_mul_f32_e32 v100, 0xbfb8aa3b, v100
	v_mul_f32_e32 v101, 0xbfb8aa3b, v101
	v_pk_add_f32 v[102:103], v[102:103], v[22:23]
	v_pk_add_f32 v[110:111], v[110:111], v[30:31]
	v_mul_f32_e32 v102, 0xbfb8aa3b, v102
	v_mul_f32_e32 v103, 0xbfb8aa3b, v103
	v_pk_add_f32 v[96:97], v[96:97], v[16:17]
	v_pk_add_f32 v[104:105], v[104:105], v[24:25]
	v_mul_f32_e32 v96, 0xbfb8aa3b, v96
	v_pk_add_f32 v[98:99], v[98:99], v[18:19]
	v_pk_add_f32 v[106:107], v[106:107], v[26:27]
	v_pk_add_f32 v[84:85], v[84:85], v[20:21]
	v_pk_add_f32 v[92:93], v[92:93], v[28:29]
	v_mul_f32_e32 v84, 0xbfb8aa3b, v84
	v_mul_f32_e32 v85, 0xbfb8aa3b, v85
	v_pk_add_f32 v[86:87], v[86:87], v[22:23]
	v_pk_add_f32 v[94:95], v[94:95], v[30:31]
	v_mul_f32_e32 v86, 0xbfb8aa3b, v86
	v_mul_f32_e32 v87, 0xbfb8aa3b, v87
	v_pk_add_f32 v[80:81], v[80:81], v[16:17]
	v_pk_add_f32 v[88:89], v[88:89], v[24:25]
	v_mul_f32_e32 v80, 0xbfb8aa3b, v80
	v_pk_add_f32 v[82:83], v[82:83], v[18:19]
	v_pk_add_f32 v[90:91], v[90:91], v[26:27]
	v_pk_add_f32 v[68:69], v[68:69], v[20:21]
	v_pk_add_f32 v[76:77], v[76:77], v[28:29]
	v_mul_f32_e32 v68, 0xbfb8aa3b, v68
	v_mul_f32_e32 v69, 0xbfb8aa3b, v69
	v_pk_add_f32 v[70:71], v[70:71], v[22:23]
	v_pk_add_f32 v[78:79], v[78:79], v[30:31]
	v_mul_f32_e32 v70, 0xbfb8aa3b, v70
	v_mul_f32_e32 v71, 0xbfb8aa3b, v71
	v_pk_add_f32 v[64:65], v[64:65], v[16:17]
	v_pk_add_f32 v[72:73], v[72:73], v[24:25]
	v_mul_f32_e32 v64, 0xbfb8aa3b, v64
	v_pk_add_f32 v[66:67], v[66:67], v[18:19]
	v_pk_add_f32 v[74:75], v[74:75], v[26:27]
	v_pk_add_f32 v[52:53], v[52:53], v[20:21]
	v_pk_add_f32 v[60:61], v[60:61], v[28:29]
	v_mul_f32_e32 v52, 0xbfb8aa3b, v52
	v_mul_f32_e32 v53, 0xbfb8aa3b, v53
	v_pk_add_f32 v[54:55], v[54:55], v[22:23]
	v_pk_add_f32 v[62:63], v[62:63], v[30:31]
	v_mul_f32_e32 v54, 0xbfb8aa3b, v54
	v_mul_f32_e32 v55, 0xbfb8aa3b, v55
	v_pk_add_f32 v[48:49], v[48:49], v[16:17]
	v_pk_add_f32 v[56:57], v[56:57], v[24:25]
	v_mul_f32_e32 v48, 0xbfb8aa3b, v48
	v_pk_add_f32 v[50:51], v[50:51], v[18:19]
	v_pk_add_f32 v[58:59], v[58:59], v[26:27]
	v_pk_add_f32 v[36:37], v[36:37], v[20:21]
	v_pk_add_f32 v[44:45], v[44:45], v[28:29]
	v_mul_f32_e32 v36, 0xbfb8aa3b, v36
	v_mul_f32_e32 v37, 0xbfb8aa3b, v37
	s_waitcnt vmcnt(7)
; __device__ __forceinline__ unsigned cvt_pk_bf16(float lo, float hi) { unsigned r; asm volatile("v_cvt_pk_bf16_f32 %0, %1, %2" : "=v"(r) : "v"(lo), "v"(hi)); return r; }
; __device__ __forceinline__ float bflo(unsigned w) { return __uint_as_float(w << 16); }
; __device__ __forceinline__ float bfhi(unsigned w) { return __uint_as_float(w & 0xffff0000u); }
; __device__ __forceinline__ float silu_f(float z) { return z / (1.0f + __expf(-z)); }
; __device__ __forceinline__ float sigmoid_f(float z) { return 1.0f / (1.0f + __expf(-z)); }
;     __device__ __forceinline__ void operator()(const AccT& acc, const Unit& u, int wr, int wc, int fr, int fq) const {
;     ...
;                 const f32x4 l0 = acc[ai][0][m][0] + bl0, l1 = acc[ai][0][m][1] + bl1, g0 = acc[ai][1][m][0] + bg0, g1 = acc[ai][1][m][1] + bg1;
;                 float o[8];
;                 o[0] = l0[0] * sigmoid_f(g0[0]) * silu_f(bflo(z.x)); o[1] = l0[1] * sigmoid_f(g0[1]) * silu_f(bfhi(z.x));
;                 o[2] = l0[2] * sigmoid_f(g0[2]) * silu_f(bflo(z.y)); o[3] = l0[3] * sigmoid_f(g0[3]) * silu_f(bfhi(z.y));
;                 o[4] = l1[0] * sigmoid_f(g1[0]) * silu_f(bflo(z.z)); o[5] = l1[1] * sigmoid_f(g1[1]) * silu_f(bfhi(z.z));
;                 o[6] = l1[2] * sigmoid_f(g1[2]) * silu_f(bflo(z.w)); o[7] = l1[3] * sigmoid_f(g1[3]) * silu_f(bfhi(z.w));
;                 u32x4 w; w.x = cvt_pk_bf16(o[0], o[1]); w.y = cvt_pk_bf16(o[2], o[3]); w.z = cvt_pk_bf16(o[4], o[5]); w.w = cvt_pk_bf16(o[6], o[7]);
;                 *(u32x4*)(OCAT + (size_t)row * 2048 + 1024 + lc) = w;
;                 if (m == 3) asm volatile("" ::: "memory");
	v_lshlrev_b32_e32 v136, 16, v128
	v_mul_f32_e32 v169, 0xbfb8aa3b, v136
	v_exp_f32_e32 v171, v169
	v_and_b32_e32 v128, 0xffff0000, v128
	v_pk_add_f32 v[38:39], v[38:39], v[22:23]
	v_pk_add_f32 v[46:47], v[46:47], v[30:31]
	v_pk_add_f32 v[170:171], v[170:171], 1.0 op_sel_hi:[1,0]
	v_mul_f32_e32 v38, 0xbfb8aa3b, v38
	v_mul_f32_e32 v39, 0xbfb8aa3b, v39
	v_pk_add_f32 v[32:33], v[32:33], v[16:17]
	v_pk_add_f32 v[40:41], v[40:41], v[24:25]
	v_rcp_f32_e32 v169, v171
	s_nop 0
	v_mul_f32_e32 v136, v136, v169
	v_mul_f32_e32 v32, 0xbfb8aa3b, v32
	v_pk_add_f32 v[34:35], v[34:35], v[18:19]
	v_pk_add_f32 v[42:43], v[42:43], v[26:27]
	v_rcp_f32_e32 v169, v170
	s_nop 0
	v_mul_f32_e32 v144, v144, v169
	v_mul_f32_e32 v144, v144, v136
	v_mul_f32_e32 v136, 0xbfb8aa3b, v137
	v_mul_f32_e32 v137, 0xbfb8aa3b, v128
	v_exp_f32_e32 v136, v136
	v_exp_f32_e32 v137, v137
	v_pk_add_f32 v[4:5], v[4:5], v[20:21]
	v_pk_add_f32 v[0:1], v[0:1], v[16:17]
	v_mul_f32_e32 v4, 0xbfb8aa3b, v4
	v_pk_add_f32 v[136:137], v[136:137], 1.0 op_sel_hi:[1,0]
	v_exp_f32_e32 v16, v4
	v_pk_add_f32 v[2:3], v[2:3], v[18:19]
	v_pk_add_f32 v[6:7], v[6:7], v[22:23]
	v_pk_add_f32 v[12:13], v[12:13], v[28:29]
	v_rcp_f32_e32 v169, v137
	s_nop 0
	v_mul_f32_e32 v128, v128, v169
	v_mul_f32_e32 v5, 0xbfb8aa3b, v5
	v_mul_f32_e32 v6, 0xbfb8aa3b, v6
	v_pk_add_f32 v[14:15], v[14:15], v[30:31]
	v_rcp_f32_e32 v136, v136
	s_nop 0
	v_mul_f32_e32 v136, v145, v136
	v_mul_f32_e32 v128, v136, v128
	v_mul_f32_e32 v136, 0xbfb8aa3b, v138
	v_lshlrev_b32_e32 v138, 16, v129
	v_mul_f32_e32 v137, 0xbfb8aa3b, v138
	v_exp_f32_e32 v136, v136
	v_exp_f32_e32 v137, v137
	v_and_b32_e32 v129, 0xffff0000, v129
	v_cvt_pk_bf16_f32 v128, v144, v128
	v_mul_f32_e32 v7, 0xbfb8aa3b, v7
	v_pk_add_f32 v[136:137], v[136:137], 1.0 op_sel_hi:[1,0]
	v_mul_f32_e32 v0, 0xbfb8aa3b, v0
	v_pk_add_f32 v[8:9], v[8:9], v[24:25]
	v_pk_add_f32 v[10:11], v[10:11], v[26:27]
	v_rcp_f32_e32 v145, v137
	s_nop 0
	v_mul_f32_e32 v137, v138, v145
	v_rcp_f32_e32 v136, v136
	s_nop 0
	v_mul_f32_e32 v136, v146, v136
	v_mul_f32_e32 v136, v136, v137
	v_mul_f32_e32 v137, 0xbfb8aa3b, v139
	v_exp_f32_e32 v138, v137
	v_mul_f32_e32 v137, 0xbfb8aa3b, v129
	v_exp_f32_e32 v139, v137
	s_nop 0
	v_pk_add_f32 v[138:139], v[138:139], 1.0 op_sel_hi:[1,0]
	s_nop 0
	v_rcp_f32_e32 v137, v139
	s_nop 0
	v_mul_f32_e32 v129, v129, v137
	v_rcp_f32_e32 v137, v138
	s_nop 0
	v_mul_f32_e32 v137, v147, v137
	v_exp_f32_e32 v138, v132
	v_lshlrev_b32_e32 v132, 16, v130
	v_mul_f32_e32 v129, v137, v129
	v_mul_f32_e32 v137, 0xbfb8aa3b, v132
	v_exp_f32_e32 v139, v137
	v_and_b32_e32 v130, 0xffff0000, v130
	v_cvt_pk_bf16_f32 v129, v136, v129
	v_exp_f32_e32 v136, v116
	v_pk_add_f32 v[138:139], v[138:139], 1.0 op_sel_hi:[1,0]
	s_nop 0
	v_rcp_f32_e32 v137, v139
	s_nop 0
	v_mul_f32_e32 v132, v132, v137
	v_rcp_f32_e32 v137, v138
	s_nop 0
	v_mul_f32_e32 v137, v140, v137
	v_mul_f32_e32 v137, v137, v132
	v_mul_f32_e32 v132, 0xbfb8aa3b, v133
	v_mul_f32_e32 v133, 0xbfb8aa3b, v130
	v_exp_f32_e32 v132, v132
	v_exp_f32_e32 v133, v133
	s_nop 0
	v_pk_add_f32 v[132:133], v[132:133], 1.0 op_sel_hi:[1,0]
	s_nop 0
	v_rcp_f32_e32 v138, v133
	s_nop 0
	v_mul_f32_e32 v130, v130, v138
	v_rcp_f32_e32 v132, v132
	s_nop 0
	v_mul_f32_e32 v132, v141, v132
	v_mul_f32_e32 v138, v132, v130
	v_mul_f32_e32 v130, 0xbfb8aa3b, v134
	v_exp_f32_e32 v132, v130
	v_lshlrev_b32_e32 v130, 16, v131
	v_mul_f32_e32 v133, 0xbfb8aa3b, v130
	v_exp_f32_e32 v133, v133
	s_nop 0
	v_pk_add_f32 v[132:133], v[132:133], 1.0 op_sel_hi:[1,0]
	s_nop 0
	v_rcp_f32_e32 v134, v133
	s_nop 0
	v_mul_f32_e32 v130, v130, v134
	v_rcp_f32_e32 v132, v132
	s_nop 0
	v_mul_f32_e32 v132, v142, v132
	v_and_b32_e32 v133, 0xffff0000, v131
	v_mul_f32_e32 v132, v132, v130
	v_mul_f32_e32 v130, 0xbfb8aa3b, v135
	v_mul_f32_e32 v131, 0xbfb8aa3b, v133
	v_exp_f32_e32 v130, v130
	v_exp_f32_e32 v131, v131
	s_nop 0
	v_pk_add_f32 v[130:131], v[130:131], 1.0 op_sel_hi:[1,0]
	s_nop 0
	v_rcp_f32_e32 v134, v131
	s_nop 0
	v_mul_f32_e32 v131, v133, v134
	v_rcp_f32_e32 v130, v130
	s_nop 0
	v_mul_f32_e32 v130, v143, v130
	v_mul_f32_e32 v131, v130, v131
	v_cvt_pk_bf16_f32 v130, v137, v138
	v_cvt_pk_bf16_f32 v131, v132, v131
	v_mad_i64_i32 v[132:133], s[30:31], v168, s66, v[162:163]
	v_lshl_add_u64 v[132:133], v[132:133], 0, v[158:159]
	v_add_co_u32_e32 v132, vcc, s67, v132
	v_or_b32_e32 v134, 16, v168
	s_nop 0
	v_addc_co_u32_e32 v133, vcc, 0, v133, vcc
	global_store_dwordx4 v[132:133], v[128:131], off offset:2048
	v_mad_i64_i32 v[132:133], s[30:31], v134, s52, v[160:161]
	s_nop 0
	v_lshl_add_u64 v[128:129], v[132:133], 0, v[158:159]
	v_add_co_u32_e32 v128, vcc, s63, v128
	s_nop 1
	v_addc_co_u32_e32 v129, vcc, 0, v129, vcc
	s_waitcnt vmcnt(7)
; __device__ __forceinline__ unsigned cvt_pk_bf16(float lo, float hi) { unsigned r; asm volatile("v_cvt_pk_bf16_f32 %0, %1, %2" : "=v"(r) : "v"(lo), "v"(hi)); return r; }
; __device__ __forceinline__ float bflo(unsigned w) { return __uint_as_float(w << 16); }
; __device__ __forceinline__ float bfhi(unsigned w) { return __uint_as_float(w & 0xffff0000u); }
; __device__ __forceinline__ float silu_f(float z) { return z / (1.0f + __expf(-z)); }
; __device__ __forceinline__ float sigmoid_f(float z) { return 1.0f / (1.0f + __expf(-z)); }
;     __device__ __forceinline__ void operator()(const AccT& acc, const Unit& u, int wr, int wc, int fr, int fq) const {
;     ...
;                 const f32x4 l0 = acc[ai][0][m][0] + bl0, l1 = acc[ai][0][m][1] + bl1, g0 = acc[ai][1][m][0] + bg0, g1 = acc[ai][1][m][1] + bg1;
;                 float o[8];
;                 o[0] = l0[0] * sigmoid_f(g0[0]) * silu_f(bflo(z.x)); o[1] = l0[1] * sigmoid_f(g0[1]) * silu_f(bfhi(z.x));
;                 o[2] = l0[2] * sigmoid_f(g0[2]) * silu_f(bflo(z.y)); o[3] = l0[3] * sigmoid_f(g0[3]) * silu_f(bfhi(z.y));
;                 o[4] = l1[0] * sigmoid_f(g1[0]) * silu_f(bflo(z.z)); o[5] = l1[1] * sigmoid_f(g1[1]) * silu_f(bfhi(z.z));
;                 o[6] = l1[2] * sigmoid_f(g1[2]) * silu_f(bflo(z.w)); o[7] = l1[3] * sigmoid_f(g1[3]) * silu_f(bfhi(z.w));
;                 u32x4 w; w.x = cvt_pk_bf16(o[0], o[1]); w.y = cvt_pk_bf16(o[2], o[3]); w.z = cvt_pk_bf16(o[4], o[5]); w.w = cvt_pk_bf16(o[6], o[7]);
;                 *(u32x4*)(OCAT + (size_t)row * 2048 + 1024 + lc) = w;
;                 if (m == 3) asm volatile("" ::: "memory");
	v_mov_b64_e32 v[128:129], v[176:177]
	v_mov_b64_e32 v[130:131], v[178:179]
	v_lshlrev_b32_e32 v116, 16, v128
	v_mul_f32_e32 v135, 0xbfb8aa3b, v116
	v_exp_f32_e32 v137, v135
	s_nop 0
	v_pk_add_f32 v[136:137], v[136:137], 1.0 op_sel_hi:[1,0]
	s_nop 0
	v_rcp_f32_e32 v135, v137
	s_nop 0
	v_mul_f32_e32 v116, v116, v135
	v_rcp_f32_e32 v135, v136
	s_nop 0
	v_mul_f32_e32 v124, v124, v135
	v_exp_f32_e32 v136, v117
	v_and_b32_e32 v117, 0xffff0000, v128
	v_mul_f32_e32 v116, v124, v116
	v_mul_f32_e32 v124, 0xbfb8aa3b, v117
	v_exp_f32_e32 v137, v124
	s_nop 0
	v_pk_add_f32 v[136:137], v[136:137], 1.0 op_sel_hi:[1,0]
	s_nop 0
	v_rcp_f32_e32 v124, v137
	s_nop 0
	v_mul_f32_e32 v117, v117, v124
	v_rcp_f32_e32 v124, v136
	s_nop 0
	v_mul_f32_e32 v124, v125, v124
	v_mul_f32_e32 v117, v124, v117
	v_exp_f32_e32 v124, v118
	v_lshlrev_b32_e32 v118, 16, v129
	v_mul_f32_e32 v125, 0xbfb8aa3b, v118
	v_exp_f32_e32 v125, v125
	s_nop 0
	v_pk_add_f32 v[124:125], v[124:125], 1.0 op_sel_hi:[1,0]
	s_nop 0
	v_rcp_f32_e32 v128, v125
	s_nop 0
	v_mul_f32_e32 v118, v118, v128
	v_rcp_f32_e32 v124, v124
	s_nop 0
	v_mul_f32_e32 v124, v126, v124
	v_mul_f32_e32 v118, v124, v118
	v_exp_f32_e32 v124, v119
	v_and_b32_e32 v119, 0xffff0000, v129
	v_mul_f32_e32 v125, 0xbfb8aa3b, v119
	v_exp_f32_e32 v125, v125
	s_nop 0
	v_pk_add_f32 v[124:125], v[124:125], 1.0 op_sel_hi:[1,0]
	s_nop 0
	v_rcp_f32_e32 v126, v125
	s_nop 0
	v_mul_f32_e32 v119, v119, v126
	v_rcp_f32_e32 v124, v124
	s_nop 0
	v_mul_f32_e32 v124, v127, v124
	v_mul_f32_e32 v119, v124, v119
	v_exp_f32_e32 v124, v112
	v_lshlrev_b32_e32 v112, 16, v130
	v_mul_f32_e32 v125, 0xbfb8aa3b, v112
	v_exp_f32_e32 v125, v125
	s_nop 0
	v_pk_add_f32 v[124:125], v[124:125], 1.0 op_sel_hi:[1,0]
	s_nop 0
	v_rcp_f32_e32 v126, v125
	s_nop 0
	v_mul_f32_e32 v112, v112, v126
	v_rcp_f32_e32 v124, v124
	s_nop 0
	v_mul_f32_e32 v120, v120, v124
	v_and_b32_e32 v124, 0xffff0000, v130
	v_mul_f32_e32 v120, v120, v112
	v_mul_f32_e32 v112, 0xbfb8aa3b, v113
	v_mul_f32_e32 v113, 0xbfb8aa3b, v124
	v_exp_f32_e32 v112, v112
	v_exp_f32_e32 v113, v113
	s_nop 0
	v_pk_add_f32 v[112:113], v[112:113], 1.0 op_sel_hi:[1,0]
	s_nop 0
	v_rcp_f32_e32 v125, v113
	s_nop 0
	v_mul_f32_e32 v113, v124, v125
	v_rcp_f32_e32 v112, v112
	s_nop 0
	v_mul_f32_e32 v112, v121, v112
	v_mul_f32_e32 v121, v112, v113
	v_mul_f32_e32 v112, 0xbfb8aa3b, v114
	v_lshlrev_b32_e32 v114, 16, v131
	v_mul_f32_e32 v113, 0xbfb8aa3b, v114
	v_exp_f32_e32 v112, v112
	v_exp_f32_e32 v113, v113
	s_nop 0
	v_pk_add_f32 v[112:113], v[112:113], 1.0 op_sel_hi:[1,0]
	s_nop 0
	v_rcp_f32_e32 v124, v113
	s_nop 0
	v_mul_f32_e32 v113, v114, v124
	v_rcp_f32_e32 v112, v112
	s_nop 0
	v_mul_f32_e32 v112, v122, v112
	v_and_b32_e32 v114, 0xffff0000, v131
	v_mul_f32_e32 v122, v112, v113
	v_mul_f32_e32 v112, 0xbfb8aa3b, v115
	v_mul_f32_e32 v113, 0xbfb8aa3b, v114
	v_exp_f32_e32 v112, v112
	v_exp_f32_e32 v113, v113
	s_nop 0
	v_pk_add_f32 v[112:113], v[112:113], 1.0 op_sel_hi:[1,0]
	s_nop 0
	v_rcp_f32_e32 v115, v113
	s_nop 0
	v_mul_f32_e32 v113, v114, v115
	v_rcp_f32_e32 v112, v112
	s_nop 0
	v_mul_f32_e32 v112, v123, v112
	v_mul_f32_e32 v115, v112, v113
	v_cvt_pk_bf16_f32 v112, v116, v117
	v_mad_i64_i32 v[116:117], s[30:31], v134, s66, v[132:133]
	v_lshl_add_u64 v[116:117], v[116:117], 0, v[158:159]
	v_add_co_u32_e32 v116, vcc, s67, v116
	v_cvt_pk_bf16_f32 v113, v118, v119
	v_or_b32_e32 v118, 32, v168
	s_nop 0
	v_addc_co_u32_e32 v117, vcc, 0, v117, vcc
	v_cvt_pk_bf16_f32 v114, v120, v121
	v_cvt_pk_bf16_f32 v115, v122, v115
	global_store_dwordx4 v[116:117], v[112:115], off offset:2048
	v_mad_i64_i32 v[116:117], s[30:31], v118, s52, v[160:161]
	s_nop 0
	v_lshl_add_u64 v[112:113], v[116:117], 0, v[158:159]
	v_add_co_u32_e32 v112, vcc, s63, v112
	v_exp_f32_e32 v120, v100
	s_nop 0
	v_addc_co_u32_e32 v113, vcc, 0, v113, vcc
	s_waitcnt vmcnt(7)
	v_mov_b64_e32 v[112:113], v[180:181]
	v_mov_b64_e32 v[114:115], v[182:183]
	v_lshlrev_b32_e32 v100, 16, v112
	v_mul_f32_e32 v119, 0xbfb8aa3b, v100
	v_exp_f32_e32 v121, v119
	s_nop 0
	v_pk_add_f32 v[120:121], v[120:121], 1.0 op_sel_hi:[1,0]
	s_nop 0
	v_rcp_f32_e32 v119, v121
	s_nop 0
	v_mul_f32_e32 v100, v100, v119
	v_rcp_f32_e32 v119, v120
	s_nop 0
	v_mul_f32_e32 v108, v108, v119
	v_exp_f32_e32 v120, v101
	v_and_b32_e32 v101, 0xffff0000, v112
	v_mul_f32_e32 v100, v108, v100
	v_mul_f32_e32 v108, 0xbfb8aa3b, v101
	v_exp_f32_e32 v121, v108
	s_nop 0
	v_pk_add_f32 v[120:121], v[120:121], 1.0 op_sel_hi:[1,0]
	s_nop 0
	v_rcp_f32_e32 v108, v121
	s_nop 0
	v_mul_f32_e32 v101, v101, v108
	v_rcp_f32_e32 v108, v120
	s_nop 0
	v_mul_f32_e32 v108, v109, v108
	v_mul_f32_e32 v101, v108, v101
	v_exp_f32_e32 v108, v102
	v_lshlrev_b32_e32 v102, 16, v113
	v_mul_f32_e32 v109, 0xbfb8aa3b, v102
	v_exp_f32_e32 v109, v109
	s_nop 0
	v_pk_add_f32 v[108:109], v[108:109], 1.0 op_sel_hi:[1,0]
	s_nop 0
	v_rcp_f32_e32 v112, v109
	s_nop 0
	v_mul_f32_e32 v102, v102, v112
	v_rcp_f32_e32 v108, v108
	s_nop 0
	v_mul_f32_e32 v108, v110, v108
	v_mul_f32_e32 v102, v108, v102
	v_exp_f32_e32 v108, v103
	v_and_b32_e32 v103, 0xffff0000, v113
	v_mul_f32_e32 v109, 0xbfb8aa3b, v103
	v_exp_f32_e32 v109, v109
	s_nop 0
	v_pk_add_f32 v[108:109], v[108:109], 1.0 op_sel_hi:[1,0]
	s_nop 0
	v_rcp_f32_e32 v110, v109
	s_nop 0
	v_mul_f32_e32 v103, v103, v110
	v_rcp_f32_e32 v108, v108
	s_nop 0
	v_mul_f32_e32 v108, v111, v108
	v_mul_f32_e32 v103, v108, v103
	v_exp_f32_e32 v108, v96
	v_lshlrev_b32_e32 v96, 16, v114
	v_mul_f32_e32 v109, 0xbfb8aa3b, v96
	v_exp_f32_e32 v109, v109
	s_nop 0
	v_pk_add_f32 v[108:109], v[108:109], 1.0 op_sel_hi:[1,0]
	s_nop 0
	v_rcp_f32_e32 v110, v109
	s_nop 0
	v_mul_f32_e32 v96, v96, v110
	v_rcp_f32_e32 v108, v108
	s_nop 0
; __device__ __forceinline__ unsigned cvt_pk_bf16(float lo, float hi) { unsigned r; asm volatile("v_cvt_pk_bf16_f32 %0, %1, %2" : "=v"(r) : "v"(lo), "v"(hi)); return r; }
; __device__ __forceinline__ float bflo(unsigned w) { return __uint_as_float(w << 16); }
; __device__ __forceinline__ float bfhi(unsigned w) { return __uint_as_float(w & 0xffff0000u); }
; __device__ __forceinline__ float silu_f(float z) { return z / (1.0f + __expf(-z)); }
; __device__ __forceinline__ float sigmoid_f(float z) { return 1.0f / (1.0f + __expf(-z)); }
;     __device__ __forceinline__ void operator()(const AccT& acc, const Unit& u, int wr, int wc, int fr, int fq) const {
;     ...
;                 const f32x4 l0 = acc[ai][0][m][0] + bl0, l1 = acc[ai][0][m][1] + bl1, g0 = acc[ai][1][m][0] + bg0, g1 = acc[ai][1][m][1] + bg1;
;                 float o[8];
;                 o[0] = l0[0] * sigmoid_f(g0[0]) * silu_f(bflo(z.x)); o[1] = l0[1] * sigmoid_f(g0[1]) * silu_f(bfhi(z.x));
;                 o[2] = l0[2] * sigmoid_f(g0[2]) * silu_f(bflo(z.y)); o[3] = l0[3] * sigmoid_f(g0[3]) * silu_f(bfhi(z.y));
;                 o[4] = l1[0] * sigmoid_f(g1[0]) * silu_f(bflo(z.z)); o[5] = l1[1] * sigmoid_f(g1[1]) * silu_f(bfhi(z.z));
;                 o[6] = l1[2] * sigmoid_f(g1[2]) * silu_f(bflo(z.w)); o[7] = l1[3] * sigmoid_f(g1[3]) * silu_f(bfhi(z.w));
;                 u32x4 w; w.x = cvt_pk_bf16(o[0], o[1]); w.y = cvt_pk_bf16(o[2], o[3]); w.z = cvt_pk_bf16(o[4], o[5]); w.w = cvt_pk_bf16(o[6], o[7]);
;                 *(u32x4*)(OCAT + (size_t)row * 2048 + 1024 + lc) = w;
;                 if (m == 3) asm volatile("" ::: "memory");
	v_mul_f32_e32 v104, v104, v108
	v_and_b32_e32 v108, 0xffff0000, v114
	v_mul_f32_e32 v104, v104, v96
	v_mul_f32_e32 v96, 0xbfb8aa3b, v97
	v_mul_f32_e32 v97, 0xbfb8aa3b, v108
	v_exp_f32_e32 v96, v96
	v_exp_f32_e32 v97, v97
	s_nop 0
	v_pk_add_f32 v[96:97], v[96:97], 1.0 op_sel_hi:[1,0]
	s_nop 0
	v_rcp_f32_e32 v109, v97
	s_nop 0
	v_mul_f32_e32 v97, v108, v109
	v_rcp_f32_e32 v96, v96
	s_nop 0
	v_mul_f32_e32 v96, v105, v96
	v_mul_f32_e32 v105, v96, v97
	v_mul_f32_e32 v96, 0xbfb8aa3b, v98
	v_lshlrev_b32_e32 v98, 16, v115
	v_mul_f32_e32 v97, 0xbfb8aa3b, v98
	v_exp_f32_e32 v96, v96
	v_exp_f32_e32 v97, v97
	s_nop 0
	v_pk_add_f32 v[96:97], v[96:97], 1.0 op_sel_hi:[1,0]
	s_nop 0
	v_rcp_f32_e32 v108, v97
	s_nop 0
	v_mul_f32_e32 v97, v98, v108
	v_rcp_f32_e32 v96, v96
	s_nop 0
	v_mul_f32_e32 v96, v106, v96
	v_and_b32_e32 v98, 0xffff0000, v115
	v_mul_f32_e32 v106, v96, v97
	v_mul_f32_e32 v96, 0xbfb8aa3b, v99
	v_mul_f32_e32 v97, 0xbfb8aa3b, v98
	v_exp_f32_e32 v96, v96
	v_exp_f32_e32 v97, v97
	s_nop 0
	v_pk_add_f32 v[96:97], v[96:97], 1.0 op_sel_hi:[1,0]
	s_nop 0
	v_rcp_f32_e32 v99, v97
	s_nop 0
	v_mul_f32_e32 v97, v98, v99
	v_rcp_f32_e32 v96, v96
	s_nop 0
	v_mul_f32_e32 v96, v107, v96
	v_mul_f32_e32 v99, v96, v97
	v_cvt_pk_bf16_f32 v96, v100, v101
	v_mad_i64_i32 v[100:101], s[30:31], v118, s66, v[116:117]
	v_lshl_add_u64 v[100:101], v[100:101], 0, v[158:159]
	v_add_co_u32_e32 v100, vcc, s67, v100
	v_cvt_pk_bf16_f32 v97, v102, v103
	v_or_b32_e32 v102, 48, v168
	s_nop 0
	v_addc_co_u32_e32 v101, vcc, 0, v101, vcc
	v_cvt_pk_bf16_f32 v98, v104, v105
	v_cvt_pk_bf16_f32 v99, v106, v99
	global_store_dwordx4 v[100:101], v[96:99], off offset:2048
	v_mad_i64_i32 v[100:101], s[30:31], v102, s52, v[160:161]
	s_nop 0
	v_lshl_add_u64 v[96:97], v[100:101], 0, v[158:159]
	v_add_co_u32_e32 v96, vcc, s63, v96
	v_exp_f32_e32 v104, v84
	s_nop 0
	v_addc_co_u32_e32 v97, vcc, 0, v97, vcc
	s_waitcnt vmcnt(7)
	v_mov_b64_e32 v[96:97], v[184:185]
	v_mov_b64_e32 v[98:99], v[186:187]
	v_lshlrev_b32_e32 v84, 16, v96
	v_mul_f32_e32 v103, 0xbfb8aa3b, v84
	v_exp_f32_e32 v105, v103
	s_nop 0
	v_pk_add_f32 v[104:105], v[104:105], 1.0 op_sel_hi:[1,0]
	s_nop 0
	v_rcp_f32_e32 v103, v105
	s_nop 0
	v_mul_f32_e32 v84, v84, v103
	v_rcp_f32_e32 v103, v104
	s_nop 0
	v_mul_f32_e32 v92, v92, v103
	v_exp_f32_e32 v104, v85
	v_and_b32_e32 v85, 0xffff0000, v96
	v_mul_f32_e32 v84, v92, v84
	v_mul_f32_e32 v92, 0xbfb8aa3b, v85
	v_exp_f32_e32 v105, v92
	s_nop 0
	v_pk_add_f32 v[104:105], v[104:105], 1.0 op_sel_hi:[1,0]
	s_nop 0
	v_rcp_f32_e32 v92, v105
	s_nop 0
	v_mul_f32_e32 v85, v85, v92
	v_rcp_f32_e32 v92, v104
	s_nop 0
	v_mul_f32_e32 v92, v93, v92
	v_mul_f32_e32 v85, v92, v85
	v_exp_f32_e32 v92, v86
	v_lshlrev_b32_e32 v86, 16, v97
	v_mul_f32_e32 v93, 0xbfb8aa3b, v86
	v_exp_f32_e32 v93, v93
	s_nop 0
	v_pk_add_f32 v[92:93], v[92:93], 1.0 op_sel_hi:[1,0]
	s_nop 0
	v_rcp_f32_e32 v96, v93
	s_nop 0
	v_mul_f32_e32 v86, v86, v96
	v_rcp_f32_e32 v92, v92
	s_nop 0
	v_mul_f32_e32 v92, v94, v92
	v_mul_f32_e32 v86, v92, v86
	v_exp_f32_e32 v92, v87
	v_and_b32_e32 v87, 0xffff0000, v97
	v_mul_f32_e32 v93, 0xbfb8aa3b, v87
	v_exp_f32_e32 v93, v93
	s_nop 0
	v_pk_add_f32 v[92:93], v[92:93], 1.0 op_sel_hi:[1,0]
	s_nop 0
	v_rcp_f32_e32 v94, v93
	s_nop 0
	v_mul_f32_e32 v87, v87, v94
	v_rcp_f32_e32 v92, v92
	s_nop 0
	v_mul_f32_e32 v92, v95, v92
	v_mul_f32_e32 v87, v92, v87
	v_exp_f32_e32 v92, v80
	v_lshlrev_b32_e32 v80, 16, v98
	v_mul_f32_e32 v93, 0xbfb8aa3b, v80
	v_exp_f32_e32 v93, v93
	s_nop 0
	v_pk_add_f32 v[92:93], v[92:93], 1.0 op_sel_hi:[1,0]
	s_nop 0
	v_rcp_f32_e32 v94, v93
	s_nop 0
	v_mul_f32_e32 v80, v80, v94
	v_rcp_f32_e32 v92, v92
	s_nop 0
	v_mul_f32_e32 v88, v88, v92
	v_and_b32_e32 v92, 0xffff0000, v98
	v_mul_f32_e32 v88, v88, v80
	v_mul_f32_e32 v80, 0xbfb8aa3b, v81
	v_mul_f32_e32 v81, 0xbfb8aa3b, v92
	v_exp_f32_e32 v80, v80
	v_exp_f32_e32 v81, v81
	s_nop 0
	v_pk_add_f32 v[80:81], v[80:81], 1.0 op_sel_hi:[1,0]
	s_nop 0
	v_rcp_f32_e32 v93, v81
	s_nop 0
	v_mul_f32_e32 v81, v92, v93
	v_rcp_f32_e32 v80, v80
	s_nop 0
	v_mul_f32_e32 v80, v89, v80
	v_mul_f32_e32 v89, v80, v81
	v_mul_f32_e32 v80, 0xbfb8aa3b, v82
	v_lshlrev_b32_e32 v82, 16, v99
	v_mul_f32_e32 v81, 0xbfb8aa3b, v82
	v_exp_f32_e32 v80, v80
	v_exp_f32_e32 v81, v81
	s_nop 0
	v_pk_add_f32 v[80:81], v[80:81], 1.0 op_sel_hi:[1,0]
	s_nop 0
	v_rcp_f32_e32 v92, v81
	s_nop 0
	v_mul_f32_e32 v81, v82, v92
	v_rcp_f32_e32 v80, v80
	s_nop 0
	v_mul_f32_e32 v80, v90, v80
	v_and_b32_e32 v82, 0xffff0000, v99
	v_mul_f32_e32 v90, v80, v81
	v_mul_f32_e32 v80, 0xbfb8aa3b, v83
	v_mul_f32_e32 v81, 0xbfb8aa3b, v82
	v_exp_f32_e32 v80, v80
	v_exp_f32_e32 v81, v81
	s_nop 0
	v_pk_add_f32 v[80:81], v[80:81], 1.0 op_sel_hi:[1,0]
	s_nop 0
	v_rcp_f32_e32 v83, v81
	s_nop 0
	v_mul_f32_e32 v81, v82, v83
	v_rcp_f32_e32 v80, v80
	s_nop 0
	v_mul_f32_e32 v80, v91, v80
	v_mul_f32_e32 v83, v80, v81
	v_cvt_pk_bf16_f32 v80, v84, v85
	v_mad_i64_i32 v[84:85], s[30:31], v102, s66, v[100:101]
	v_lshl_add_u64 v[84:85], v[84:85], 0, v[158:159]
	v_add_co_u32_e32 v84, vcc, s67, v84
	v_cvt_pk_bf16_f32 v81, v86, v87
	v_add_u32_e32 v86, 0x80, v168
	s_nop 0
	v_addc_co_u32_e32 v85, vcc, 0, v85, vcc
	v_cvt_pk_bf16_f32 v82, v88, v89
	v_cvt_pk_bf16_f32 v83, v90, v83
	global_store_dwordx4 v[84:85], v[80:83], off offset:2048
	v_mad_i64_i32 v[84:85], s[30:31], v86, s52, v[160:161]
	s_nop 0
	v_lshl_add_u64 v[80:81], v[84:85], 0, v[158:159]
	v_add_co_u32_e32 v80, vcc, s63, v80
	v_exp_f32_e32 v88, v68
	s_nop 0
	v_addc_co_u32_e32 v81, vcc, 0, v81, vcc
	s_waitcnt vmcnt(7)
; __device__ __forceinline__ unsigned cvt_pk_bf16(float lo, float hi) { unsigned r; asm volatile("v_cvt_pk_bf16_f32 %0, %1, %2" : "=v"(r) : "v"(lo), "v"(hi)); return r; }
; __device__ __forceinline__ float bflo(unsigned w) { return __uint_as_float(w << 16); }
; __device__ __forceinline__ float bfhi(unsigned w) { return __uint_as_float(w & 0xffff0000u); }
; __device__ __forceinline__ float silu_f(float z) { return z / (1.0f + __expf(-z)); }
; __device__ __forceinline__ float sigmoid_f(float z) { return 1.0f / (1.0f + __expf(-z)); }
;     __device__ __forceinline__ void operator()(const AccT& acc, const Unit& u, int wr, int wc, int fr, int fq) const {
;     ...
;                 const f32x4 l0 = acc[ai][0][m][0] + bl0, l1 = acc[ai][0][m][1] + bl1, g0 = acc[ai][1][m][0] + bg0, g1 = acc[ai][1][m][1] + bg1;
;                 float o[8];
;                 o[0] = l0[0] * sigmoid_f(g0[0]) * silu_f(bflo(z.x)); o[1] = l0[1] * sigmoid_f(g0[1]) * silu_f(bfhi(z.x));
;                 o[2] = l0[2] * sigmoid_f(g0[2]) * silu_f(bflo(z.y)); o[3] = l0[3] * sigmoid_f(g0[3]) * silu_f(bfhi(z.y));
;                 o[4] = l1[0] * sigmoid_f(g1[0]) * silu_f(bflo(z.z)); o[5] = l1[1] * sigmoid_f(g1[1]) * silu_f(bfhi(z.z));
;                 o[6] = l1[2] * sigmoid_f(g1[2]) * silu_f(bflo(z.w)); o[7] = l1[3] * sigmoid_f(g1[3]) * silu_f(bfhi(z.w));
;                 u32x4 w; w.x = cvt_pk_bf16(o[0], o[1]); w.y = cvt_pk_bf16(o[2], o[3]); w.z = cvt_pk_bf16(o[4], o[5]); w.w = cvt_pk_bf16(o[6], o[7]);
;                 *(u32x4*)(OCAT + (size_t)row * 2048 + 1024 + lc) = w;
;                 if (m == 3) asm volatile("" ::: "memory");
	v_mov_b64_e32 v[80:81], v[188:189]
	v_mov_b64_e32 v[82:83], v[190:191]
	v_lshlrev_b32_e32 v68, 16, v80
	v_mul_f32_e32 v87, 0xbfb8aa3b, v68
	v_exp_f32_e32 v89, v87
	s_nop 0
	v_pk_add_f32 v[88:89], v[88:89], 1.0 op_sel_hi:[1,0]
	s_nop 0
	v_rcp_f32_e32 v87, v89
	s_nop 0
	v_mul_f32_e32 v68, v68, v87
	v_rcp_f32_e32 v87, v88
	s_nop 0
	v_mul_f32_e32 v76, v76, v87
	v_exp_f32_e32 v88, v69
	v_and_b32_e32 v69, 0xffff0000, v80
	v_mul_f32_e32 v68, v76, v68
	v_mul_f32_e32 v76, 0xbfb8aa3b, v69
	v_exp_f32_e32 v89, v76
	s_nop 0
	v_pk_add_f32 v[88:89], v[88:89], 1.0 op_sel_hi:[1,0]
	s_nop 0
	v_rcp_f32_e32 v76, v89
	s_nop 0
	v_mul_f32_e32 v69, v69, v76
	v_rcp_f32_e32 v76, v88
	s_nop 0
	v_mul_f32_e32 v76, v77, v76
	v_mul_f32_e32 v69, v76, v69
	v_exp_f32_e32 v76, v70
	v_lshlrev_b32_e32 v70, 16, v81
	v_mul_f32_e32 v77, 0xbfb8aa3b, v70
	v_exp_f32_e32 v77, v77
	s_nop 0
	v_pk_add_f32 v[76:77], v[76:77], 1.0 op_sel_hi:[1,0]
	s_nop 0
	v_rcp_f32_e32 v80, v77
	s_nop 0
	v_mul_f32_e32 v70, v70, v80
	v_rcp_f32_e32 v76, v76
	s_nop 0
	v_mul_f32_e32 v76, v78, v76
	v_mul_f32_e32 v70, v76, v70
	v_exp_f32_e32 v76, v71
	v_and_b32_e32 v71, 0xffff0000, v81
	v_mul_f32_e32 v77, 0xbfb8aa3b, v71
	v_exp_f32_e32 v77, v77
	s_nop 0
	v_pk_add_f32 v[76:77], v[76:77], 1.0 op_sel_hi:[1,0]
	s_nop 0
	v_rcp_f32_e32 v78, v77
	s_nop 0
	v_mul_f32_e32 v71, v71, v78
	v_rcp_f32_e32 v76, v76
	s_nop 0
	v_mul_f32_e32 v76, v79, v76
	v_mul_f32_e32 v71, v76, v71
	v_exp_f32_e32 v76, v64
	v_lshlrev_b32_e32 v64, 16, v82
	v_mul_f32_e32 v77, 0xbfb8aa3b, v64
	v_exp_f32_e32 v77, v77
	s_nop 0
	v_pk_add_f32 v[76:77], v[76:77], 1.0 op_sel_hi:[1,0]
	s_nop 0
	v_rcp_f32_e32 v78, v77
	s_nop 0
	v_mul_f32_e32 v64, v64, v78
	v_rcp_f32_e32 v76, v76
	s_nop 0
	v_mul_f32_e32 v72, v72, v76
	v_and_b32_e32 v76, 0xffff0000, v82
	v_mul_f32_e32 v72, v72, v64
	v_mul_f32_e32 v64, 0xbfb8aa3b, v65
	v_mul_f32_e32 v65, 0xbfb8aa3b, v76
	v_exp_f32_e32 v64, v64
	v_exp_f32_e32 v65, v65
	s_nop 0
	v_pk_add_f32 v[64:65], v[64:65], 1.0 op_sel_hi:[1,0]
	s_nop 0
	v_rcp_f32_e32 v77, v65
	s_nop 0
	v_mul_f32_e32 v65, v76, v77
	v_rcp_f32_e32 v64, v64
	s_nop 0
	v_mul_f32_e32 v64, v73, v64
	v_mul_f32_e32 v73, v64, v65
	v_mul_f32_e32 v64, 0xbfb8aa3b, v66
	v_lshlrev_b32_e32 v66, 16, v83
	v_mul_f32_e32 v65, 0xbfb8aa3b, v66
	v_exp_f32_e32 v64, v64
	v_exp_f32_e32 v65, v65
	s_nop 0
	v_pk_add_f32 v[64:65], v[64:65], 1.0 op_sel_hi:[1,0]
	s_nop 0
	v_rcp_f32_e32 v76, v65
	s_nop 0
	v_mul_f32_e32 v65, v66, v76
	v_rcp_f32_e32 v64, v64
	s_nop 0
	v_mul_f32_e32 v64, v74, v64
	v_and_b32_e32 v66, 0xffff0000, v83
	v_mul_f32_e32 v74, v64, v65
	v_mul_f32_e32 v64, 0xbfb8aa3b, v67
	v_mul_f32_e32 v65, 0xbfb8aa3b, v66
	v_exp_f32_e32 v64, v64
	v_exp_f32_e32 v65, v65
	s_nop 0
	v_pk_add_f32 v[64:65], v[64:65], 1.0 op_sel_hi:[1,0]
	s_nop 0
	v_rcp_f32_e32 v67, v65
	s_nop 0
	v_mul_f32_e32 v65, v66, v67
	v_rcp_f32_e32 v64, v64
	s_nop 0
	v_mul_f32_e32 v64, v75, v64
	v_mul_f32_e32 v67, v64, v65
	v_cvt_pk_bf16_f32 v64, v68, v69
	v_mad_i64_i32 v[68:69], s[30:31], v86, s66, v[84:85]
	v_lshl_add_u64 v[68:69], v[68:69], 0, v[158:159]
	v_add_co_u32_e32 v68, vcc, s67, v68
	v_cvt_pk_bf16_f32 v65, v70, v71
	v_add_u32_e32 v70, 0x90, v168
	s_nop 0
	v_addc_co_u32_e32 v69, vcc, 0, v69, vcc
	v_cvt_pk_bf16_f32 v66, v72, v73
	v_cvt_pk_bf16_f32 v67, v74, v67
	global_store_dwordx4 v[68:69], v[64:67], off offset:2048
	v_mad_i64_i32 v[68:69], s[30:31], v70, s52, v[160:161]
	s_nop 0
	v_lshl_add_u64 v[64:65], v[68:69], 0, v[158:159]
	v_add_co_u32_e32 v64, vcc, s63, v64
	v_exp_f32_e32 v72, v52
	s_nop 0
	v_addc_co_u32_e32 v65, vcc, 0, v65, vcc
	s_waitcnt vmcnt(7)
	v_mov_b64_e32 v[64:65], v[192:193]
	v_mov_b64_e32 v[66:67], v[194:195]
	v_lshlrev_b32_e32 v52, 16, v64
	v_mul_f32_e32 v71, 0xbfb8aa3b, v52
	v_exp_f32_e32 v73, v71
	s_nop 0
	v_pk_add_f32 v[72:73], v[72:73], 1.0 op_sel_hi:[1,0]
	s_nop 0
	v_rcp_f32_e32 v71, v73
	s_nop 0
	v_mul_f32_e32 v52, v52, v71
	v_rcp_f32_e32 v71, v72
	s_nop 0
	v_mul_f32_e32 v60, v60, v71
	v_exp_f32_e32 v72, v53
	v_and_b32_e32 v53, 0xffff0000, v64
	v_mul_f32_e32 v52, v60, v52
	v_mul_f32_e32 v60, 0xbfb8aa3b, v53
	v_exp_f32_e32 v73, v60
	s_nop 0
	v_pk_add_f32 v[72:73], v[72:73], 1.0 op_sel_hi:[1,0]
	s_nop 0
	v_rcp_f32_e32 v60, v73
	s_nop 0
	v_mul_f32_e32 v53, v53, v60
	v_rcp_f32_e32 v60, v72
	s_nop 0
	v_mul_f32_e32 v60, v61, v60
	v_mul_f32_e32 v53, v60, v53
	v_exp_f32_e32 v60, v54
	v_lshlrev_b32_e32 v54, 16, v65
	v_mul_f32_e32 v61, 0xbfb8aa3b, v54
	v_exp_f32_e32 v61, v61
	s_nop 0
	v_pk_add_f32 v[60:61], v[60:61], 1.0 op_sel_hi:[1,0]
	s_nop 0
	v_rcp_f32_e32 v64, v61
	s_nop 0
	v_mul_f32_e32 v54, v54, v64
	v_rcp_f32_e32 v60, v60
	s_nop 0
	v_mul_f32_e32 v60, v62, v60
	v_mul_f32_e32 v54, v60, v54
	v_exp_f32_e32 v60, v55
	v_and_b32_e32 v55, 0xffff0000, v65
	v_mul_f32_e32 v61, 0xbfb8aa3b, v55
	v_exp_f32_e32 v61, v61
	s_nop 0
	v_pk_add_f32 v[60:61], v[60:61], 1.0 op_sel_hi:[1,0]
	s_nop 0
	v_rcp_f32_e32 v62, v61
	s_nop 0
	v_mul_f32_e32 v55, v55, v62
	v_rcp_f32_e32 v60, v60
	s_nop 0
	v_mul_f32_e32 v60, v63, v60
	v_mul_f32_e32 v55, v60, v55
	v_exp_f32_e32 v60, v48
	v_lshlrev_b32_e32 v48, 16, v66
	v_mul_f32_e32 v61, 0xbfb8aa3b, v48
	v_exp_f32_e32 v61, v61
	s_nop 0
	v_pk_add_f32 v[60:61], v[60:61], 1.0 op_sel_hi:[1,0]
	s_nop 0
	v_rcp_f32_e32 v62, v61
	s_nop 0
	v_mul_f32_e32 v48, v48, v62
	v_rcp_f32_e32 v60, v60
	s_nop 0
	v_mul_f32_e32 v56, v56, v60
	v_and_b32_e32 v60, 0xffff0000, v66
	v_mul_f32_e32 v56, v56, v48
	v_mul_f32_e32 v48, 0xbfb8aa3b, v49
	v_mul_f32_e32 v49, 0xbfb8aa3b, v60
	v_exp_f32_e32 v48, v48
	v_exp_f32_e32 v49, v49
	s_nop 0
	v_pk_add_f32 v[48:49], v[48:49], 1.0 op_sel_hi:[1,0]
	s_nop 0
	v_rcp_f32_e32 v61, v49
	s_nop 0
	v_mul_f32_e32 v49, v60, v61
	v_rcp_f32_e32 v48, v48
	s_nop 0
; __device__ __forceinline__ unsigned cvt_pk_bf16(float lo, float hi) { unsigned r; asm volatile("v_cvt_pk_bf16_f32 %0, %1, %2" : "=v"(r) : "v"(lo), "v"(hi)); return r; }
; __device__ __forceinline__ float bflo(unsigned w) { return __uint_as_float(w << 16); }
; __device__ __forceinline__ float bfhi(unsigned w) { return __uint_as_float(w & 0xffff0000u); }
; __device__ __forceinline__ float silu_f(float z) { return z / (1.0f + __expf(-z)); }
; __device__ __forceinline__ float sigmoid_f(float z) { return 1.0f / (1.0f + __expf(-z)); }
;     __device__ __forceinline__ void operator()(const AccT& acc, const Unit& u, int wr, int wc, int fr, int fq) const {
;     ...
;                 const f32x4 l0 = acc[ai][0][m][0] + bl0, l1 = acc[ai][0][m][1] + bl1, g0 = acc[ai][1][m][0] + bg0, g1 = acc[ai][1][m][1] + bg1;
;                 float o[8];
;                 o[0] = l0[0] * sigmoid_f(g0[0]) * silu_f(bflo(z.x)); o[1] = l0[1] * sigmoid_f(g0[1]) * silu_f(bfhi(z.x));
;                 o[2] = l0[2] * sigmoid_f(g0[2]) * silu_f(bflo(z.y)); o[3] = l0[3] * sigmoid_f(g0[3]) * silu_f(bfhi(z.y));
;                 o[4] = l1[0] * sigmoid_f(g1[0]) * silu_f(bflo(z.z)); o[5] = l1[1] * sigmoid_f(g1[1]) * silu_f(bfhi(z.z));
;                 o[6] = l1[2] * sigmoid_f(g1[2]) * silu_f(bflo(z.w)); o[7] = l1[3] * sigmoid_f(g1[3]) * silu_f(bfhi(z.w));
;                 u32x4 w; w.x = cvt_pk_bf16(o[0], o[1]); w.y = cvt_pk_bf16(o[2], o[3]); w.z = cvt_pk_bf16(o[4], o[5]); w.w = cvt_pk_bf16(o[6], o[7]);
;                 *(u32x4*)(OCAT + (size_t)row * 2048 + 1024 + lc) = w;
;                 if (m == 3) asm volatile("" ::: "memory");
	v_mul_f32_e32 v48, v57, v48
	v_mul_f32_e32 v57, v48, v49
	v_mul_f32_e32 v48, 0xbfb8aa3b, v50
	v_lshlrev_b32_e32 v50, 16, v67
	v_mul_f32_e32 v49, 0xbfb8aa3b, v50
	v_exp_f32_e32 v48, v48
	v_exp_f32_e32 v49, v49
	s_nop 0
	v_pk_add_f32 v[48:49], v[48:49], 1.0 op_sel_hi:[1,0]
	s_nop 0
	v_rcp_f32_e32 v60, v49
	s_nop 0
	v_mul_f32_e32 v49, v50, v60
	v_rcp_f32_e32 v48, v48
	s_nop 0
	v_mul_f32_e32 v48, v58, v48
	v_and_b32_e32 v50, 0xffff0000, v67
	v_mul_f32_e32 v58, v48, v49
	v_mul_f32_e32 v48, 0xbfb8aa3b, v51
	v_mul_f32_e32 v49, 0xbfb8aa3b, v50
	v_exp_f32_e32 v48, v48
	v_exp_f32_e32 v49, v49
	s_nop 0
	v_pk_add_f32 v[48:49], v[48:49], 1.0 op_sel_hi:[1,0]
	s_nop 0
	v_rcp_f32_e32 v51, v49
	s_nop 0
	v_mul_f32_e32 v49, v50, v51
	v_rcp_f32_e32 v48, v48
	s_nop 0
	v_mul_f32_e32 v48, v59, v48
	v_mul_f32_e32 v51, v48, v49
	v_cvt_pk_bf16_f32 v48, v52, v53
	v_mad_i64_i32 v[52:53], s[30:31], v70, s66, v[68:69]
	v_lshl_add_u64 v[52:53], v[52:53], 0, v[158:159]
	v_add_co_u32_e32 v52, vcc, s67, v52
	v_cvt_pk_bf16_f32 v49, v54, v55
	v_add_u32_e32 v54, 0xa0, v168
	s_nop 0
	v_addc_co_u32_e32 v53, vcc, 0, v53, vcc
	v_cvt_pk_bf16_f32 v50, v56, v57
	v_cvt_pk_bf16_f32 v51, v58, v51
	global_store_dwordx4 v[52:53], v[48:51], off offset:2048
	v_mad_i64_i32 v[52:53], s[30:31], v54, s52, v[160:161]
	s_nop 0
	v_lshl_add_u64 v[48:49], v[52:53], 0, v[158:159]
	v_add_co_u32_e32 v48, vcc, s63, v48
	v_exp_f32_e32 v56, v36
	s_nop 0
	v_addc_co_u32_e32 v49, vcc, 0, v49, vcc
	s_waitcnt vmcnt(7)
	v_mov_b64_e32 v[48:49], v[196:197]
	v_mov_b64_e32 v[50:51], v[198:199]
	v_lshlrev_b32_e32 v36, 16, v48
	v_mul_f32_e32 v55, 0xbfb8aa3b, v36
	v_exp_f32_e32 v57, v55
	s_nop 0
	v_pk_add_f32 v[56:57], v[56:57], 1.0 op_sel_hi:[1,0]
	s_nop 0
	v_rcp_f32_e32 v55, v57
	s_nop 0
	v_mul_f32_e32 v36, v36, v55
	v_rcp_f32_e32 v55, v56
	s_nop 0
	v_mul_f32_e32 v44, v44, v55
	v_exp_f32_e32 v56, v37
	v_and_b32_e32 v37, 0xffff0000, v48
	v_mul_f32_e32 v36, v44, v36
	v_mul_f32_e32 v44, 0xbfb8aa3b, v37
	v_exp_f32_e32 v57, v44
	s_nop 0
	v_pk_add_f32 v[56:57], v[56:57], 1.0 op_sel_hi:[1,0]
	s_nop 0
	v_rcp_f32_e32 v44, v57
	s_nop 0
	v_mul_f32_e32 v37, v37, v44
	v_rcp_f32_e32 v44, v56
	s_nop 0
	v_mul_f32_e32 v44, v45, v44
	v_mul_f32_e32 v37, v44, v37
	v_exp_f32_e32 v44, v38
	v_lshlrev_b32_e32 v38, 16, v49
	v_mul_f32_e32 v45, 0xbfb8aa3b, v38
	v_exp_f32_e32 v45, v45
	s_nop 0
	v_pk_add_f32 v[44:45], v[44:45], 1.0 op_sel_hi:[1,0]
	s_nop 0
	v_rcp_f32_e32 v48, v45
	s_nop 0
	v_mul_f32_e32 v38, v38, v48
	v_rcp_f32_e32 v44, v44
	s_nop 0
	v_mul_f32_e32 v44, v46, v44
	v_mul_f32_e32 v38, v44, v38
	v_exp_f32_e32 v44, v39
	v_and_b32_e32 v39, 0xffff0000, v49
	v_mul_f32_e32 v45, 0xbfb8aa3b, v39
	v_exp_f32_e32 v45, v45
	s_nop 0
	v_pk_add_f32 v[44:45], v[44:45], 1.0 op_sel_hi:[1,0]
	s_nop 0
	v_rcp_f32_e32 v46, v45
	s_nop 0
	v_mul_f32_e32 v39, v39, v46
	v_rcp_f32_e32 v44, v44
	s_nop 0
	v_mul_f32_e32 v44, v47, v44
	v_mul_f32_e32 v39, v44, v39
	v_exp_f32_e32 v44, v32
	v_lshlrev_b32_e32 v32, 16, v50
	v_mul_f32_e32 v45, 0xbfb8aa3b, v32
	v_exp_f32_e32 v45, v45
	s_nop 0
	v_pk_add_f32 v[44:45], v[44:45], 1.0 op_sel_hi:[1,0]
	s_nop 0
	v_rcp_f32_e32 v46, v45
	s_nop 0
	v_mul_f32_e32 v32, v32, v46
	v_rcp_f32_e32 v44, v44
	s_nop 0
	v_mul_f32_e32 v40, v40, v44
	v_and_b32_e32 v44, 0xffff0000, v50
	v_mul_f32_e32 v40, v40, v32
	v_mul_f32_e32 v32, 0xbfb8aa3b, v33
	v_mul_f32_e32 v33, 0xbfb8aa3b, v44
	v_exp_f32_e32 v32, v32
	v_exp_f32_e32 v33, v33
	s_nop 0
	v_pk_add_f32 v[32:33], v[32:33], 1.0 op_sel_hi:[1,0]
	s_nop 0
	v_rcp_f32_e32 v45, v33
	s_nop 0
	v_mul_f32_e32 v33, v44, v45
	v_rcp_f32_e32 v32, v32
	s_nop 0
	v_mul_f32_e32 v32, v41, v32
	v_mul_f32_e32 v41, v32, v33
	v_mul_f32_e32 v32, 0xbfb8aa3b, v34
	v_lshlrev_b32_e32 v34, 16, v51
	v_mul_f32_e32 v33, 0xbfb8aa3b, v34
	v_exp_f32_e32 v32, v32
	v_exp_f32_e32 v33, v33
	s_nop 0
	v_pk_add_f32 v[32:33], v[32:33], 1.0 op_sel_hi:[1,0]
	s_nop 0
	v_rcp_f32_e32 v44, v33
	s_nop 0
	v_mul_f32_e32 v33, v34, v44
	v_rcp_f32_e32 v32, v32
	s_nop 0
	v_mul_f32_e32 v32, v42, v32
	v_and_b32_e32 v34, 0xffff0000, v51
	v_mul_f32_e32 v42, v32, v33
	v_mul_f32_e32 v32, 0xbfb8aa3b, v35
	v_mul_f32_e32 v33, 0xbfb8aa3b, v34
	v_exp_f32_e32 v32, v32
	v_exp_f32_e32 v33, v33
	s_nop 0
	v_pk_add_f32 v[32:33], v[32:33], 1.0 op_sel_hi:[1,0]
	s_nop 0
	v_rcp_f32_e32 v35, v33
	s_nop 0
	v_mul_f32_e32 v33, v34, v35
	v_rcp_f32_e32 v32, v32
	s_nop 0
	v_mul_f32_e32 v32, v43, v32
	v_mul_f32_e32 v35, v32, v33
	v_cvt_pk_bf16_f32 v32, v36, v37
	v_mad_i64_i32 v[36:37], s[30:31], v54, s66, v[52:53]
	v_lshl_add_u64 v[36:37], v[36:37], 0, v[158:159]
	v_add_co_u32_e32 v36, vcc, s67, v36
	v_cvt_pk_bf16_f32 v33, v38, v39
	v_add_u32_e32 v38, 0xb0, v168
	s_nop 0
	v_addc_co_u32_e32 v37, vcc, 0, v37, vcc
	v_cvt_pk_bf16_f32 v34, v40, v41
	v_cvt_pk_bf16_f32 v35, v42, v35
	global_store_dwordx4 v[36:37], v[32:35], off offset:2048
	v_mad_i64_i32 v[36:37], s[30:31], v38, s52, v[160:161]
	s_nop 0
	v_lshl_add_u64 v[32:33], v[36:37], 0, v[158:159]
	v_add_co_u32_e32 v32, vcc, s63, v32
	s_nop 1
	v_addc_co_u32_e32 v33, vcc, 0, v33, vcc
	s_waitcnt vmcnt(7)
; __device__ __forceinline__ unsigned cvt_pk_bf16(float lo, float hi) { unsigned r; asm volatile("v_cvt_pk_bf16_f32 %0, %1, %2" : "=v"(r) : "v"(lo), "v"(hi)); return r; }
; __device__ __forceinline__ float bflo(unsigned w) { return __uint_as_float(w << 16); }
; __device__ __forceinline__ float bfhi(unsigned w) { return __uint_as_float(w & 0xffff0000u); }
; __device__ __forceinline__ float silu_f(float z) { return z / (1.0f + __expf(-z)); }
; __device__ __forceinline__ float sigmoid_f(float z) { return 1.0f / (1.0f + __expf(-z)); }
; #define PG8_BAR __builtin_amdgcn_s_barrier()
; template <bool SP2 = true, class Epi, class Sched>
; __device__ __forceinline__ void gemm_phase(LAS unsigned char* lds, const int K, const int lda, const int ldb, const Sched& S, const Epi& E) {
;     ...
;         if (!has_next) break;
; #pragma unroll
;         for (int a = 0; a < 2; ++a)
; #pragma unroll
;             for (int b = 0; b < 2; ++b)
; #pragma unroll
;                 for (int m = 0; m < 4; ++m)
; #pragma unroll
;                     for (int n = 0; n < 2; ++n) acc[a][b][m][n] = (f32x4){0.f, 0.f, 0.f, 0.f};
;         cur = nxt; cA = nA; cB = nB; ++ui;
;         if (wr == 1) PG8_BAR;
;     __device__ __forceinline__ void operator()(const AccT& acc, const Unit& u, int wr, int wc, int fr, int fq) const {
;     ...
;                 const f32x4 l0 = acc[ai][0][m][0] + bl0, l1 = acc[ai][0][m][1] + bl1, g0 = acc[ai][1][m][0] + bg0, g1 = acc[ai][1][m][1] + bg1;
;                 float o[8];
;                 o[0] = l0[0] * sigmoid_f(g0[0]) * silu_f(bflo(z.x)); o[1] = l0[1] * sigmoid_f(g0[1]) * silu_f(bfhi(z.x));
;                 o[2] = l0[2] * sigmoid_f(g0[2]) * silu_f(bflo(z.y)); o[3] = l0[3] * sigmoid_f(g0[3]) * silu_f(bfhi(z.y));
;                 o[4] = l1[0] * sigmoid_f(g1[0]) * silu_f(bflo(z.z)); o[5] = l1[1] * sigmoid_f(g1[1]) * silu_f(bfhi(z.z));
;                 o[6] = l1[2] * sigmoid_f(g1[2]) * silu_f(bflo(z.w)); o[7] = l1[3] * sigmoid_f(g1[3]) * silu_f(bfhi(z.w));
;                 u32x4 w; w.x = cvt_pk_bf16(o[0], o[1]); w.y = cvt_pk_bf16(o[2], o[3]); w.z = cvt_pk_bf16(o[4], o[5]); w.w = cvt_pk_bf16(o[6], o[7]);
;                 *(u32x4*)(OCAT + (size_t)row * 2048 + 1024 + lc) = w;
;                 if (m == 3) asm volatile("" ::: "memory");
;             }
	v_mov_b64_e32 v[32:33], v[200:201]
	v_mov_b64_e32 v[34:35], v[202:203]
	v_lshlrev_b32_e32 v4, 16, v32
	v_mul_f32_e32 v17, 0xbfb8aa3b, v4
	v_exp_f32_e32 v17, v17
	s_nop 0
	v_pk_add_f32 v[16:17], v[16:17], 1.0 op_sel_hi:[1,0]
	s_nop 0
	v_rcp_f32_e32 v18, v17
	s_nop 0
	v_mul_f32_e32 v4, v4, v18
	v_rcp_f32_e32 v16, v16
	s_nop 0
	v_mul_f32_e32 v12, v12, v16
	v_exp_f32_e32 v16, v5
	v_and_b32_e32 v5, 0xffff0000, v32
	v_mul_f32_e32 v4, v12, v4
	v_mul_f32_e32 v12, 0xbfb8aa3b, v5
	v_exp_f32_e32 v17, v12
	s_nop 0
	v_pk_add_f32 v[16:17], v[16:17], 1.0 op_sel_hi:[1,0]
	s_nop 0
	v_rcp_f32_e32 v12, v17
	s_nop 0
	v_mul_f32_e32 v5, v5, v12
	v_rcp_f32_e32 v12, v16
	s_nop 0
	v_mul_f32_e32 v12, v13, v12
	v_mul_f32_e32 v5, v12, v5
	v_exp_f32_e32 v12, v6
	v_lshlrev_b32_e32 v6, 16, v33
	v_mul_f32_e32 v13, 0xbfb8aa3b, v6
	v_exp_f32_e32 v13, v13
	s_nop 0
	v_pk_add_f32 v[12:13], v[12:13], 1.0 op_sel_hi:[1,0]
	s_nop 0
	v_rcp_f32_e32 v16, v13
	s_nop 0
	v_mul_f32_e32 v6, v6, v16
	v_rcp_f32_e32 v12, v12
	s_nop 0
	v_mul_f32_e32 v12, v14, v12
	v_mul_f32_e32 v6, v12, v6
	v_exp_f32_e32 v12, v7
	v_and_b32_e32 v7, 0xffff0000, v33
	v_mul_f32_e32 v13, 0xbfb8aa3b, v7
	v_exp_f32_e32 v13, v13
	s_nop 0
	v_pk_add_f32 v[12:13], v[12:13], 1.0 op_sel_hi:[1,0]
	s_nop 0
	v_rcp_f32_e32 v14, v13
	s_nop 0
	v_mul_f32_e32 v7, v7, v14
	v_rcp_f32_e32 v12, v12
	s_nop 0
	v_mul_f32_e32 v12, v15, v12
	v_mul_f32_e32 v7, v12, v7
	v_exp_f32_e32 v12, v0
	v_lshlrev_b32_e32 v0, 16, v34
	v_mul_f32_e32 v13, 0xbfb8aa3b, v0
	v_exp_f32_e32 v13, v13
	s_nop 0
	v_pk_add_f32 v[12:13], v[12:13], 1.0 op_sel_hi:[1,0]
	s_nop 0
	v_rcp_f32_e32 v14, v13
	s_nop 0
	v_mul_f32_e32 v0, v0, v14
	v_rcp_f32_e32 v12, v12
	s_nop 0
	v_mul_f32_e32 v8, v8, v12
	v_and_b32_e32 v12, 0xffff0000, v34
	v_mul_f32_e32 v8, v8, v0
	v_mul_f32_e32 v0, 0xbfb8aa3b, v1
	v_mul_f32_e32 v1, 0xbfb8aa3b, v12
	v_exp_f32_e32 v0, v0
	v_exp_f32_e32 v1, v1
	s_nop 0
	v_pk_add_f32 v[0:1], v[0:1], 1.0 op_sel_hi:[1,0]
	s_nop 0
	v_rcp_f32_e32 v13, v1
	s_nop 0
	v_mul_f32_e32 v1, v12, v13
	v_rcp_f32_e32 v0, v0
	s_nop 0
	v_mul_f32_e32 v0, v9, v0
	v_mul_f32_e32 v9, v0, v1
	v_mul_f32_e32 v0, 0xbfb8aa3b, v2
	v_lshlrev_b32_e32 v2, 16, v35
	v_mul_f32_e32 v1, 0xbfb8aa3b, v2
	v_exp_f32_e32 v0, v0
	v_exp_f32_e32 v1, v1
	s_nop 0
	v_pk_add_f32 v[0:1], v[0:1], 1.0 op_sel_hi:[1,0]
	s_nop 0
	v_rcp_f32_e32 v12, v1
	s_nop 0
	v_mul_f32_e32 v1, v2, v12
	v_rcp_f32_e32 v0, v0
	s_nop 0
	v_mul_f32_e32 v0, v10, v0
	v_and_b32_e32 v2, 0xffff0000, v35
	v_mul_f32_e32 v10, v0, v1
	v_mul_f32_e32 v0, 0xbfb8aa3b, v3
	v_mul_f32_e32 v1, 0xbfb8aa3b, v2
	v_exp_f32_e32 v0, v0
	v_exp_f32_e32 v1, v1
	s_nop 0
	v_pk_add_f32 v[0:1], v[0:1], 1.0 op_sel_hi:[1,0]
	s_nop 0
	v_rcp_f32_e32 v3, v1
	s_nop 0
	v_mul_f32_e32 v1, v2, v3
	v_rcp_f32_e32 v0, v0
	s_nop 0
	v_mul_f32_e32 v0, v11, v0
	v_mul_f32_e32 v3, v0, v1
	v_cvt_pk_bf16_f32 v0, v4, v5
	v_mad_i64_i32 v[4:5], s[30:31], v38, s66, v[36:37]
	v_lshl_add_u64 v[4:5], v[4:5], 0, v[158:159]
	v_add_co_u32_e32 v4, vcc, 0xca00000, v4
	v_cvt_pk_bf16_f32 v1, v6, v7
	v_cvt_pk_bf16_f32 v2, v8, v9
	v_cvt_pk_bf16_f32 v3, v10, v3
	s_mov_b64 s[30:31], -1
	s_nop 0
	v_addc_co_u32_e32 v5, vcc, 0, v5, vcc
	global_store_dwordx4 v[4:5], v[0:3], off offset:2048
	s_andn2_b64 vcc, exec, s[4:5]
	s_cbranch_vccnz .LBB0_598
	s_andn2_b64 vcc, exec, s[8:9]
	s_cbranch_vccnz .LBB0_597
	s_barrier
	s_branch .LBB0_597
